# pool-phase epilogue: the four (gate, pool_scale) vector pairs loaded together, one wait (was four serialized round trips)
# speedup vs baseline: 1.0104x; 1.0104x over previous
.LBB0_1205:
	s_ashr_i32 s40, s42, 5
	v_lshl_or_b32 v160, s8, 8, v175
	s_mul_i32 s8, s40, 0x6000
	s_mul_hi_i32 s9, s40, 0x6000
	s_add_u32 s8, s55, s8
	s_addc_u32 s9, s58, s9
	v_ashrrev_i32_e32 v161, 31, v160
	v_lshl_add_u64 v[30:31], v[160:161], 2, s[8:9]
	global_load_dwordx4 v[18:21], v[30:31], off
	v_cndmask_b32_e64 v0, 0, 1, s[22:23]
	v_cmp_ne_u32_e64 s[8:9], 1, v0
	s_andn2_b64 vcc, exec, s[22:23]
	v_lshl_add_u64 v[158:159], v[160:161], 2, s[56:57]
	global_load_dwordx4 v[22:25], v[30:31], off offset:16
	global_load_dwordx4 v[26:29], v[30:31], off offset:512
	v_readlane_b32 s84, v255, 6
	global_load_dwordx4 v[30:33], v[30:31], off offset:528
	v_readlane_b32 s85, v255, 7
	v_readlane_b32 s86, v255, 8
	v_readlane_b32 s87, v255, 9
	s_cbranch_vccnz .LBB0_1213
	global_load_dwordx4 v[204:207], v[158:159], off
	global_load_dwordx4 v[208:211], v[158:159], off offset:16
	global_load_dwordx4 v[212:215], v[158:159], off offset:512
	global_load_dwordx4 v[216:219], v[158:159], off offset:528
	s_waitcnt vmcnt(0)
	v_pk_mul_f32 v[20:21], v[20:21], v[206:207]
	v_pk_mul_f32 v[18:19], v[18:19], v[204:205]
	v_pk_mul_f32 v[24:25], v[24:25], v[210:211]
	v_pk_mul_f32 v[22:23], v[22:23], v[208:209]
	v_pk_mul_f32 v[28:29], v[28:29], v[214:215]
	v_pk_mul_f32 v[26:27], v[26:27], v[212:213]
	v_pk_mul_f32 v[32:33], v[32:33], v[218:219]
	v_pk_mul_f32 v[30:31], v[30:31], v[216:217]
